# attention fast loops: one static s_setprio 1 for waves 4-7 (reset at loop exit); on top of attention DMA/VALU trims
# speedup vs baseline: 1.0038x; 1.0038x over previous
; __device__ __forceinline__ void diff_unit(const bf16* proj, bf16* og0, const float* nwv, float lam_full, float one_m_li, int h, int qb, ldsp lds, int tid, int lane, int wave, int mode) {
;     ...
; #pragma unroll
;     for (int i = 0; i < 3; ++i) { const int n = i < nt ? i : nt - 1; dma_tile(kbase, vbase, 64 * DIFF_TILE(n), lds + i * RSTG, wave, lane); }
; #pragma unroll 1
;     for (int i = 0; i < 2; ++i) {
;         asm volatile("s_waitcnt vmcnt(8)" ::: "memory");
;         __builtin_amdgcn_s_barrier();
;         asm volatile("" ::: "memory");
;         { int n = i + 3; n = n < nt ? n : nt - 1; dma_tile(kbase, vbase, 64 * DIFF_TILE(n), lds + ((i + 3) & 3) * RSTG, wave, lane); }
;         ldsp Ks = lds + (i & 3) * RSTG, Vs = Ks + RKV;
; #pragma unroll 1
;         for (int hh = 0; hh < 2; ++hh) flash_half2<4>(Ks + hh * 32 * 256, Vs + hh * 32 * 256, M, qf, o, mc, l, 64 * (td + i) + 32 * hh, qi, qmin, 1 << 30, lane);
;     }
; #pragma unroll 1
;     for (int i = 2; i < nt; ++i) {
;         asm volatile("s_waitcnt vmcnt(8)" ::: "memory");
;         __builtin_amdgcn_s_barrier();
;         asm volatile("" ::: "memory");
;         { int n = i + 3; n = n < nt ? n : nt - 1; dma_tile(kbase, vbase, 64 * (n - 2), lds + ((i + 3) & 3) * RSTG, wave, lane); }
;         ldsp Ks = lds + (i & 3) * RSTG, Vs = Ks + RKV;
;         flash_fast_tile2<4>(Ks, Vs, M, qf, o, mc, l);
.LBB0_433:
	s_mov_b32 s6, 2
	s_add_i32 s7, s9, 2
	s_or_b32 s8, s9, 1
	s_cmp_lt_u32 5, s7
	s_cselect_b32 s1, 5, s8
	v_lshl_add_u32 v223, s1, 6, v183
	v_add_u32_e32 v225, s35, v223
	v_add_u32_e32 v223, s31, v223
	v_lshlrev_b32_e32 v225, 8, v225
	v_lshlrev_b32_e32 v223, 8, v223
	v_lshl_add_u32 v225, v156, 1, v225
	v_lshl_add_u32 v223, v154, 1, v223
	s_and_b64 vcc, exec, s[20:21]
	s_cbranch_vccz .Lap_skip1
	s_setprio 1
.Lap_skip1:
	s_branch .LBB0_435

; #define LAS __attribute__((address_space(3)))
; __device__ __forceinline__ int crow(int r, int hi) { return (r & 3) + 8 * (r >> 2) + 4 * hi; }
; __device__ __forceinline__ float xsum32(float v) { auto rr = __builtin_amdgcn_permlane32_swap(__float_as_uint(v), __float_as_uint(v), false, false); return __uint_as_float(rr[0]) + __uint_as_float(rr[1]); }
; __device__ __forceinline__ void diff_unit(const bf16* proj, bf16* og0, const float* nwv, float lam_full, float one_m_li, int h, int qb, ldsp lds, int tid, int lane, int wave, int mode) {
;     ...
;     asm volatile("s_waitcnt vmcnt(0)" ::: "memory");
;     l = xsum32(l);
;     const float inv = 1.f / l;
;     __syncthreads();
;     LAS float* X = (LAS float*)lds;
;     if (wg == 1) {
; #pragma unroll
;         for (int b = 0; b < 4; ++b)
; #pragma unroll
;             for (int r = 0; r < 16; ++r) X[(32 * wq + r32) * 129 + 32 * b + crow(r, hi)] = o[b][r] * inv;
.LBB0_441:
	s_setprio 0
	v_mov_b32_e32 v66, v195
	s_nop 1
	v_permlane32_swap_b32_e32 v195, v66
	v_add_f32_e32 v66, v195, v66
	v_div_scale_f32 v67, s[0:1], v66, v66, 1.0
	v_rcp_f32_e32 v68, v67
	s_waitcnt vmcnt(0)
	s_barrier
	v_fma_f32 v69, -v67, v68, 1.0
	v_fmac_f32_e32 v68, v69, v68
	v_div_scale_f32 v69, vcc, 1.0, v66, 1.0
	v_mul_f32_e32 v70, v69, v68
	v_fma_f32 v71, -v67, v70, v69
	v_fmac_f32_e32 v70, v71, v68
	v_fma_f32 v67, -v67, v70, v69
	v_div_fmas_f32 v67, v67, v68, v70
	v_div_fixup_f32 v78, v67, v66, 1.0
	v_cndmask_b32_e64 v66, 0, 1, s[20:21]
	v_cmp_ne_u32_e64 s[8:9], 1, v66
	s_andn2_b64 vcc, exec, s[20:21]
	s_cbranch_vccnz .LBB0_443
	v_pk_mul_f32 v[66:67], v[50:51], v[78:79] op_sel_hi:[1,0]
	ds_write2_b32 v185, v66, v67 offset1:1
	v_pk_mul_f32 v[66:67], v[52:53], v[78:79] op_sel_hi:[1,0]
	ds_write2_b32 v185, v66, v67 offset0:2 offset1:3
	v_pk_mul_f32 v[66:67], v[54:55], v[78:79] op_sel_hi:[1,0]
	ds_write2_b32 v185, v66, v67 offset0:8 offset1:9
	v_pk_mul_f32 v[66:67], v[56:57], v[78:79] op_sel_hi:[1,0]
	ds_write2_b32 v185, v66, v67 offset0:10 offset1:11
	v_pk_mul_f32 v[66:67], v[58:59], v[78:79] op_sel_hi:[1,0]
	ds_write2_b32 v185, v66, v67 offset0:16 offset1:17
	v_pk_mul_f32 v[66:67], v[60:61], v[78:79] op_sel_hi:[1,0]
	ds_write2_b32 v185, v66, v67 offset0:18 offset1:19
	v_pk_mul_f32 v[66:67], v[62:63], v[78:79] op_sel_hi:[1,0]
	ds_write2_b32 v185, v66, v67 offset0:24 offset1:25
	v_pk_mul_f32 v[66:67], v[64:65], v[78:79] op_sel_hi:[1,0]
	ds_write2_b32 v185, v66, v67 offset0:26 offset1:27
	v_pk_mul_f32 v[66:67], v[34:35], v[78:79] op_sel_hi:[1,0]
	ds_write2_b32 v185, v66, v67 offset0:32 offset1:33
	v_pk_mul_f32 v[66:67], v[36:37], v[78:79] op_sel_hi:[1,0]
	ds_write2_b32 v185, v66, v67 offset0:34 offset1:35
	v_pk_mul_f32 v[66:67], v[38:39], v[78:79] op_sel_hi:[1,0]
	ds_write2_b32 v185, v66, v67 offset0:40 offset1:41
	v_pk_mul_f32 v[66:67], v[40:41], v[78:79] op_sel_hi:[1,0]
	ds_write2_b32 v185, v66, v67 offset0:42 offset1:43
	v_pk_mul_f32 v[66:67], v[42:43], v[78:79] op_sel_hi:[1,0]
	ds_write2_b32 v185, v66, v67 offset0:48 offset1:49
	v_pk_mul_f32 v[66:67], v[44:45], v[78:79] op_sel_hi:[1,0]
	ds_write2_b32 v185, v66, v67 offset0:50 offset1:51
	v_pk_mul_f32 v[66:67], v[46:47], v[78:79] op_sel_hi:[1,0]
	ds_write2_b32 v185, v66, v67 offset0:56 offset1:57
	v_pk_mul_f32 v[66:67], v[48:49], v[78:79] op_sel_hi:[1,0]
	ds_write2_b32 v185, v66, v67 offset0:58 offset1:59
	v_pk_mul_f32 v[66:67], v[18:19], v[78:79] op_sel_hi:[1,0]
	ds_write2_b32 v185, v66, v67 offset0:64 offset1:65
	v_pk_mul_f32 v[66:67], v[20:21], v[78:79] op_sel_hi:[1,0]
	ds_write2_b32 v185, v66, v67 offset0:66 offset1:67
	v_pk_mul_f32 v[66:67], v[22:23], v[78:79] op_sel_hi:[1,0]
	ds_write2_b32 v185, v66, v67 offset0:72 offset1:73
	v_pk_mul_f32 v[66:67], v[24:25], v[78:79] op_sel_hi:[1,0]
	ds_write2_b32 v185, v66, v67 offset0:74 offset1:75
	v_pk_mul_f32 v[66:67], v[26:27], v[78:79] op_sel_hi:[1,0]
	ds_write2_b32 v185, v66, v67 offset0:80 offset1:81
	v_pk_mul_f32 v[66:67], v[28:29], v[78:79] op_sel_hi:[1,0]
	ds_write2_b32 v185, v66, v67 offset0:82 offset1:83
	v_pk_mul_f32 v[66:67], v[30:31], v[78:79] op_sel_hi:[1,0]
	ds_write2_b32 v185, v66, v67 offset0:88 offset1:89
	v_pk_mul_f32 v[66:67], v[32:33], v[78:79] op_sel_hi:[1,0]
	ds_write2_b32 v185, v66, v67 offset0:90 offset1:91
	v_pk_mul_f32 v[66:67], v[2:3], v[78:79] op_sel_hi:[1,0]
	ds_write2_b32 v185, v66, v67 offset0:96 offset1:97
	v_pk_mul_f32 v[66:67], v[4:5], v[78:79] op_sel_hi:[1,0]
	ds_write2_b32 v185, v66, v67 offset0:98 offset1:99
	v_pk_mul_f32 v[66:67], v[6:7], v[78:79] op_sel_hi:[1,0]
	ds_write2_b32 v185, v66, v67 offset0:104 offset1:105
	v_pk_mul_f32 v[66:67], v[8:9], v[78:79] op_sel_hi:[1,0]
	ds_write2_b32 v185, v66, v67 offset0:106 offset1:107
	v_pk_mul_f32 v[66:67], v[10:11], v[78:79] op_sel_hi:[1,0]
	ds_write2_b32 v185, v66, v67 offset0:112 offset1:113
	v_pk_mul_f32 v[66:67], v[12:13], v[78:79] op_sel_hi:[1,0]
	ds_write2_b32 v185, v66, v67 offset0:114 offset1:115
	v_pk_mul_f32 v[66:67], v[14:15], v[78:79] op_sel_hi:[1,0]
	ds_write2_b32 v185, v66, v67 offset0:120 offset1:121
	v_pk_mul_f32 v[66:67], v[16:17], v[78:79] op_sel_hi:[1,0]
	ds_write2_b32 v185, v66, v67 offset0:122 offset1:123

; __device__ __forceinline__ void diff_unit(const bf16* proj, bf16* og0, const float* nwv, float lam_full, float one_m_li, int h, int qb, ldsp lds, int tid, int lane, int wave, int mode) {
;     ...
; #pragma unroll
;     for (int i = 0; i < 3; ++i) { const int n = i < nt ? i : nt - 1; dma_tile(kbase, vbase, 64 * DIFF_TILE(n), lds + i * RSTG, wave, lane); }
; #pragma unroll 1
;     for (int i = 0; i < 2; ++i) {
;         asm volatile("s_waitcnt vmcnt(8)" ::: "memory");
;         __builtin_amdgcn_s_barrier();
;         asm volatile("" ::: "memory");
;         { int n = i + 3; n = n < nt ? n : nt - 1; dma_tile(kbase, vbase, 64 * DIFF_TILE(n), lds + ((i + 3) & 3) * RSTG, wave, lane); }
;         ldsp Ks = lds + (i & 3) * RSTG, Vs = Ks + RKV;
; #pragma unroll 1
;         for (int hh = 0; hh < 2; ++hh) flash_half2<4>(Ks + hh * 32 * 256, Vs + hh * 32 * 256, M, qf, o, mc, l, 64 * (td + i) + 32 * hh, qi, qmin, 1 << 30, lane);
;     }
; #pragma unroll 1
;     for (int i = 2; i < nt; ++i) {
;         asm volatile("s_waitcnt vmcnt(8)" ::: "memory");
;         __builtin_amdgcn_s_barrier();
;         asm volatile("" ::: "memory");
;         { int n = i + 3; n = n < nt ? n : nt - 1; dma_tile(kbase, vbase, 64 * (n - 2), lds + ((i + 3) & 3) * RSTG, wave, lane); }
;         ldsp Ks = lds + (i & 3) * RSTG, Vs = Ks + RKV;
;         flash_fast_tile2<4>(Ks, Vs, M, qf, o, mc, l);
.LBB0_456:
	s_andn2_b64 vcc, exec, s[28:29]
	s_cbranch_vccnz .LBB0_465
	s_mov_b32 s6, 2
	s_cmp_lt_i32 5, s59
	s_cselect_b32 s1, 5, s60
	v_lshl_add_u32 v223, s1, 6, v183
	v_add_u32_e32 v225, s35, v223
	v_add_u32_e32 v223, s31, v223
	v_lshlrev_b32_e32 v225, 8, v225
	v_lshlrev_b32_e32 v223, 8, v223
	v_lshl_add_u32 v225, v156, 1, v225
	v_lshl_add_u32 v223, v154, 1, v223
	s_and_b64 vcc, exec, s[20:21]
	s_cbranch_vccz .Lap_skip2
	s_setprio 1

; #define LAS __attribute__((address_space(3)))
; __device__ __forceinline__ int crow(int r, int hi) { return (r & 3) + 8 * (r >> 2) + 4 * hi; }
; __device__ __forceinline__ float xsum32(float v) { auto rr = __builtin_amdgcn_permlane32_swap(__float_as_uint(v), __float_as_uint(v), false, false); return __uint_as_float(rr[0]) + __uint_as_float(rr[1]); }
; __device__ __forceinline__ void diff_unit(const bf16* proj, bf16* og0, const float* nwv, float lam_full, float one_m_li, int h, int qb, ldsp lds, int tid, int lane, int wave, int mode) {
;     ...
;     asm volatile("s_waitcnt vmcnt(0)" ::: "memory");
;     l = xsum32(l);
;     const float inv = 1.f / l;
;     __syncthreads();
;     LAS float* X = (LAS float*)lds;
;     if (wg == 1) {
; #pragma unroll
;         for (int b = 0; b < 4; ++b)
; #pragma unroll
;             for (int r = 0; r < 16; ++r) X[(32 * wq + r32) * 129 + 32 * b + crow(r, hi)] = o[b][r] * inv;
.LBB0_465:
	s_setprio 0
	v_mov_b32_e32 v0, v195
	s_nop 1
	v_permlane32_swap_b32_e32 v195, v0
	v_add_f32_e32 v0, v195, v0
	v_div_scale_f32 v2, s[0:1], v0, v0, 1.0
	v_rcp_f32_e32 v3, v2
	s_waitcnt vmcnt(0)
	s_barrier
	v_fma_f32 v4, -v2, v3, 1.0
	v_fmac_f32_e32 v3, v4, v3
	v_div_scale_f32 v4, vcc, 1.0, v0, 1.0
	v_mul_f32_e32 v5, v4, v3
	v_fma_f32 v6, -v2, v5, v4
	v_fmac_f32_e32 v5, v6, v3
	v_fma_f32 v2, -v2, v5, v4
	v_div_fmas_f32 v2, v2, v3, v5
	v_div_fixup_f32 v0, v2, v0, 1.0
	s_and_b64 vcc, exec, s[8:9]
	s_cbranch_vccnz .LBB0_467
	v_pk_mul_f32 v[2:3], v[64:65], v[0:1] op_sel_hi:[1,0]
	ds_write2_b32 v185, v2, v3 offset1:1
	v_pk_mul_f32 v[2:3], v[66:67], v[0:1] op_sel_hi:[1,0]
	ds_write2_b32 v185, v2, v3 offset0:2 offset1:3
	v_pk_mul_f32 v[2:3], v[68:69], v[0:1] op_sel_hi:[1,0]
	ds_write2_b32 v185, v2, v3 offset0:8 offset1:9
	v_pk_mul_f32 v[2:3], v[70:71], v[0:1] op_sel_hi:[1,0]
	ds_write2_b32 v185, v2, v3 offset0:10 offset1:11
	v_pk_mul_f32 v[2:3], v[72:73], v[0:1] op_sel_hi:[1,0]
	ds_write2_b32 v185, v2, v3 offset0:16 offset1:17
	v_pk_mul_f32 v[2:3], v[74:75], v[0:1] op_sel_hi:[1,0]
	ds_write2_b32 v185, v2, v3 offset0:18 offset1:19
	v_pk_mul_f32 v[2:3], v[76:77], v[0:1] op_sel_hi:[1,0]
	ds_write2_b32 v185, v2, v3 offset0:24 offset1:25
	v_pk_mul_f32 v[2:3], v[78:79], v[0:1] op_sel_hi:[1,0]
	ds_write2_b32 v185, v2, v3 offset0:26 offset1:27
	v_pk_mul_f32 v[2:3], v[48:49], v[0:1] op_sel_hi:[1,0]
	ds_write2_b32 v185, v2, v3 offset0:32 offset1:33
	v_pk_mul_f32 v[2:3], v[50:51], v[0:1] op_sel_hi:[1,0]
	ds_write2_b32 v185, v2, v3 offset0:34 offset1:35
	v_pk_mul_f32 v[2:3], v[52:53], v[0:1] op_sel_hi:[1,0]
	ds_write2_b32 v185, v2, v3 offset0:40 offset1:41
	v_pk_mul_f32 v[2:3], v[54:55], v[0:1] op_sel_hi:[1,0]
	ds_write2_b32 v185, v2, v3 offset0:42 offset1:43
	v_pk_mul_f32 v[2:3], v[56:57], v[0:1] op_sel_hi:[1,0]
	ds_write2_b32 v185, v2, v3 offset0:48 offset1:49
	v_pk_mul_f32 v[2:3], v[58:59], v[0:1] op_sel_hi:[1,0]
	ds_write2_b32 v185, v2, v3 offset0:50 offset1:51
	v_pk_mul_f32 v[2:3], v[60:61], v[0:1] op_sel_hi:[1,0]
	ds_write2_b32 v185, v2, v3 offset0:56 offset1:57
	v_pk_mul_f32 v[2:3], v[62:63], v[0:1] op_sel_hi:[1,0]
	ds_write2_b32 v185, v2, v3 offset0:58 offset1:59
	v_pk_mul_f32 v[2:3], v[32:33], v[0:1] op_sel_hi:[1,0]
	ds_write2_b32 v185, v2, v3 offset0:64 offset1:65
	v_pk_mul_f32 v[2:3], v[34:35], v[0:1] op_sel_hi:[1,0]
	ds_write2_b32 v185, v2, v3 offset0:66 offset1:67
	v_pk_mul_f32 v[2:3], v[36:37], v[0:1] op_sel_hi:[1,0]
	ds_write2_b32 v185, v2, v3 offset0:72 offset1:73
	v_pk_mul_f32 v[2:3], v[38:39], v[0:1] op_sel_hi:[1,0]
	ds_write2_b32 v185, v2, v3 offset0:74 offset1:75
	v_pk_mul_f32 v[2:3], v[40:41], v[0:1] op_sel_hi:[1,0]
	ds_write2_b32 v185, v2, v3 offset0:80 offset1:81
	v_pk_mul_f32 v[2:3], v[42:43], v[0:1] op_sel_hi:[1,0]
	ds_write2_b32 v185, v2, v3 offset0:82 offset1:83
	v_pk_mul_f32 v[2:3], v[44:45], v[0:1] op_sel_hi:[1,0]
	ds_write2_b32 v185, v2, v3 offset0:88 offset1:89
	v_pk_mul_f32 v[2:3], v[46:47], v[0:1] op_sel_hi:[1,0]
	ds_write2_b32 v185, v2, v3 offset0:90 offset1:91
	v_pk_mul_f32 v[2:3], v[16:17], v[0:1] op_sel_hi:[1,0]
	ds_write2_b32 v185, v2, v3 offset0:96 offset1:97
	v_pk_mul_f32 v[2:3], v[18:19], v[0:1] op_sel_hi:[1,0]
	ds_write2_b32 v185, v2, v3 offset0:98 offset1:99
	v_pk_mul_f32 v[2:3], v[20:21], v[0:1] op_sel_hi:[1,0]
	ds_write2_b32 v185, v2, v3 offset0:104 offset1:105
	v_pk_mul_f32 v[2:3], v[22:23], v[0:1] op_sel_hi:[1,0]
	ds_write2_b32 v185, v2, v3 offset0:106 offset1:107
	v_pk_mul_f32 v[2:3], v[24:25], v[0:1] op_sel_hi:[1,0]
	ds_write2_b32 v185, v2, v3 offset0:112 offset1:113
	v_pk_mul_f32 v[2:3], v[26:27], v[0:1] op_sel_hi:[1,0]
	ds_write2_b32 v185, v2, v3 offset0:114 offset1:115
	v_pk_mul_f32 v[2:3], v[28:29], v[0:1] op_sel_hi:[1,0]
	ds_write2_b32 v185, v2, v3 offset0:120 offset1:121
	v_pk_mul_f32 v[2:3], v[30:31], v[0:1] op_sel_hi:[1,0]
	ds_write2_b32 v185, v2, v3 offset0:122 offset1:123
